# EpiResid epilogues (G2,G4) rewritten: 16 loads in flight + counted vmcnt instead of load/vmcnt(0)/store chain
# speedup vs baseline: 1.0058x; 1.0058x over previous
.LBB0_538:
	v_mov_b32_e32 v140, v142
	v_lshl_or_b32 v146, s68, 8, v144
	v_lshl_add_u32 v140, s69, 8, v140
	v_lshl_add_u32 v140, v140, 10, v146
	v_lshlrev_b32_e32 v140, 2, v140
	s_mov_b64 s[8:9], 0xb0000
	s_mov_b64 s[50:51], -1
	s_and_b64 vcc, exec, s[38:39]
	v_add_u32_e32 v141, 0x10000, v140
	v_add_u32_e32 v186, 0x20000, v140
	v_add_u32_e32 v187, 0x30000, v140
	v_add_u32_e32 v202, 0x80000, v140
	v_add_u32_e32 v203, 0x90000, v140
	v_add_u32_e32 v248, 0xa0000, v140
	v_add_u32_e32 v249, 0xb0000, v140
	global_load_dwordx4 v[146:149], v140, s[42:43]
	global_load_dwordx4 v[150:153], v140, s[42:43] offset:16
	global_load_dwordx4 v[154:157], v140, s[42:43] offset:512
	global_load_dwordx4 v[158:161], v140, s[42:43] offset:528
	global_load_dwordx4 v[162:165], v141, s[42:43]
	global_load_dwordx4 v[166:169], v141, s[42:43] offset:16
	global_load_dwordx4 v[170:173], v141, s[42:43] offset:512
	global_load_dwordx4 v[174:177], v141, s[42:43] offset:528
	global_load_dwordx4 v[178:181], v186, s[42:43]
	global_load_dwordx4 v[182:185], v186, s[42:43] offset:16
	global_load_dwordx4 v[224:227], v186, s[42:43] offset:512
	global_load_dwordx4 v[228:231], v186, s[42:43] offset:528
	global_load_dwordx4 v[232:235], v187, s[42:43]
	global_load_dwordx4 v[236:239], v187, s[42:43] offset:16
	global_load_dwordx4 v[240:243], v187, s[42:43] offset:512
	global_load_dwordx4 v[244:247], v187, s[42:43] offset:528
	s_waitcnt vmcnt(12)
	v_pk_fma_f32 v[126:127], v[126:127], 0.5, v[146:147] op_sel_hi:[1,0,1]
	v_pk_fma_f32 v[128:129], v[128:129], 0.5, v[148:149] op_sel_hi:[1,0,1]
	v_pk_fma_f32 v[122:123], v[122:123], 0.5, v[150:151] op_sel_hi:[1,0,1]
	v_pk_fma_f32 v[124:125], v[124:125], 0.5, v[152:153] op_sel_hi:[1,0,1]
	v_pk_fma_f32 v[118:119], v[118:119], 0.5, v[154:155] op_sel_hi:[1,0,1]
	v_pk_fma_f32 v[120:121], v[120:121], 0.5, v[156:157] op_sel_hi:[1,0,1]
	v_pk_fma_f32 v[114:115], v[114:115], 0.5, v[158:159] op_sel_hi:[1,0,1]
	v_pk_fma_f32 v[116:117], v[116:117], 0.5, v[160:161] op_sel_hi:[1,0,1]
	global_store_dwordx4 v140, v[126:129], s[24:25]
	global_store_dwordx4 v140, v[122:125], s[24:25] offset:16
	global_store_dwordx4 v140, v[118:121], s[24:25] offset:512
	global_store_dwordx4 v140, v[114:117], s[24:25] offset:528
	global_load_dwordx4 v[146:149], v202, s[42:43]
	global_load_dwordx4 v[150:153], v202, s[42:43] offset:16
	global_load_dwordx4 v[154:157], v202, s[42:43] offset:512
	global_load_dwordx4 v[158:161], v202, s[42:43] offset:528
	s_waitcnt vmcnt(16)
	v_pk_fma_f32 v[110:111], v[110:111], 0.5, v[162:163] op_sel_hi:[1,0,1]
	v_pk_fma_f32 v[112:113], v[112:113], 0.5, v[164:165] op_sel_hi:[1,0,1]
	v_pk_fma_f32 v[106:107], v[106:107], 0.5, v[166:167] op_sel_hi:[1,0,1]
	v_pk_fma_f32 v[108:109], v[108:109], 0.5, v[168:169] op_sel_hi:[1,0,1]
	v_pk_fma_f32 v[102:103], v[102:103], 0.5, v[170:171] op_sel_hi:[1,0,1]
	v_pk_fma_f32 v[104:105], v[104:105], 0.5, v[172:173] op_sel_hi:[1,0,1]
	v_pk_fma_f32 v[98:99], v[98:99], 0.5, v[174:175] op_sel_hi:[1,0,1]
	v_pk_fma_f32 v[100:101], v[100:101], 0.5, v[176:177] op_sel_hi:[1,0,1]
	global_store_dwordx4 v141, v[110:113], s[24:25]
	global_store_dwordx4 v141, v[106:109], s[24:25] offset:16
	global_store_dwordx4 v141, v[102:105], s[24:25] offset:512
	global_store_dwordx4 v141, v[98:101], s[24:25] offset:528
	global_load_dwordx4 v[162:165], v203, s[42:43]
	global_load_dwordx4 v[166:169], v203, s[42:43] offset:16
	global_load_dwordx4 v[170:173], v203, s[42:43] offset:512
	global_load_dwordx4 v[174:177], v203, s[42:43] offset:528
	s_waitcnt vmcnt(20)
	v_pk_fma_f32 v[94:95], v[94:95], 0.5, v[178:179] op_sel_hi:[1,0,1]
	v_pk_fma_f32 v[96:97], v[96:97], 0.5, v[180:181] op_sel_hi:[1,0,1]
	v_pk_fma_f32 v[90:91], v[90:91], 0.5, v[182:183] op_sel_hi:[1,0,1]
	v_pk_fma_f32 v[92:93], v[92:93], 0.5, v[184:185] op_sel_hi:[1,0,1]
	v_pk_fma_f32 v[86:87], v[86:87], 0.5, v[224:225] op_sel_hi:[1,0,1]
	v_pk_fma_f32 v[88:89], v[88:89], 0.5, v[226:227] op_sel_hi:[1,0,1]
	v_pk_fma_f32 v[82:83], v[82:83], 0.5, v[228:229] op_sel_hi:[1,0,1]
	v_pk_fma_f32 v[84:85], v[84:85], 0.5, v[230:231] op_sel_hi:[1,0,1]
	global_store_dwordx4 v186, v[94:97], s[24:25]
	global_store_dwordx4 v186, v[90:93], s[24:25] offset:16
	global_store_dwordx4 v186, v[86:89], s[24:25] offset:512
	global_store_dwordx4 v186, v[82:85], s[24:25] offset:528
	global_load_dwordx4 v[178:181], v248, s[42:43]
	global_load_dwordx4 v[182:185], v248, s[42:43] offset:16
	global_load_dwordx4 v[224:227], v248, s[42:43] offset:512
	global_load_dwordx4 v[228:231], v248, s[42:43] offset:528
	s_waitcnt vmcnt(24)
	v_pk_fma_f32 v[78:79], v[78:79], 0.5, v[232:233] op_sel_hi:[1,0,1]
	v_pk_fma_f32 v[80:81], v[80:81], 0.5, v[234:235] op_sel_hi:[1,0,1]
	v_pk_fma_f32 v[74:75], v[74:75], 0.5, v[236:237] op_sel_hi:[1,0,1]
	v_pk_fma_f32 v[76:77], v[76:77], 0.5, v[238:239] op_sel_hi:[1,0,1]
	v_pk_fma_f32 v[70:71], v[70:71], 0.5, v[240:241] op_sel_hi:[1,0,1]
	v_pk_fma_f32 v[72:73], v[72:73], 0.5, v[242:243] op_sel_hi:[1,0,1]
	v_pk_fma_f32 v[66:67], v[66:67], 0.5, v[244:245] op_sel_hi:[1,0,1]
	v_pk_fma_f32 v[68:69], v[68:69], 0.5, v[246:247] op_sel_hi:[1,0,1]
	global_store_dwordx4 v187, v[78:81], s[24:25]
	global_store_dwordx4 v187, v[74:77], s[24:25] offset:16
	global_store_dwordx4 v187, v[70:73], s[24:25] offset:512
	global_store_dwordx4 v187, v[66:69], s[24:25] offset:528
	global_load_dwordx4 v[232:235], v249, s[42:43]
	global_load_dwordx4 v[236:239], v249, s[42:43] offset:16
	global_load_dwordx4 v[240:243], v249, s[42:43] offset:512
	global_load_dwordx4 v[244:247], v249, s[42:43] offset:528
	s_waitcnt vmcnt(24)
	v_pk_fma_f32 v[62:63], v[62:63], 0.5, v[146:147] op_sel_hi:[1,0,1]
	v_pk_fma_f32 v[64:65], v[64:65], 0.5, v[148:149] op_sel_hi:[1,0,1]
	v_pk_fma_f32 v[58:59], v[58:59], 0.5, v[150:151] op_sel_hi:[1,0,1]
	v_pk_fma_f32 v[60:61], v[60:61], 0.5, v[152:153] op_sel_hi:[1,0,1]
	v_pk_fma_f32 v[54:55], v[54:55], 0.5, v[154:155] op_sel_hi:[1,0,1]
	v_pk_fma_f32 v[56:57], v[56:57], 0.5, v[156:157] op_sel_hi:[1,0,1]
	v_pk_fma_f32 v[50:51], v[50:51], 0.5, v[158:159] op_sel_hi:[1,0,1]
	v_pk_fma_f32 v[52:53], v[52:53], 0.5, v[160:161] op_sel_hi:[1,0,1]
	global_store_dwordx4 v202, v[62:65], s[24:25]
	global_store_dwordx4 v202, v[58:61], s[24:25] offset:16
	global_store_dwordx4 v202, v[54:57], s[24:25] offset:512
	global_store_dwordx4 v202, v[50:53], s[24:25] offset:528
	s_waitcnt vmcnt(20)
	v_pk_fma_f32 v[46:47], v[46:47], 0.5, v[162:163] op_sel_hi:[1,0,1]
	v_pk_fma_f32 v[48:49], v[48:49], 0.5, v[164:165] op_sel_hi:[1,0,1]
	v_pk_fma_f32 v[42:43], v[42:43], 0.5, v[166:167] op_sel_hi:[1,0,1]
	v_pk_fma_f32 v[44:45], v[44:45], 0.5, v[168:169] op_sel_hi:[1,0,1]
	v_pk_fma_f32 v[38:39], v[38:39], 0.5, v[170:171] op_sel_hi:[1,0,1]
	v_pk_fma_f32 v[40:41], v[40:41], 0.5, v[172:173] op_sel_hi:[1,0,1]
	v_pk_fma_f32 v[34:35], v[34:35], 0.5, v[174:175] op_sel_hi:[1,0,1]
	v_pk_fma_f32 v[36:37], v[36:37], 0.5, v[176:177] op_sel_hi:[1,0,1]
	global_store_dwordx4 v203, v[46:49], s[24:25]
	global_store_dwordx4 v203, v[42:45], s[24:25] offset:16
	global_store_dwordx4 v203, v[38:41], s[24:25] offset:512
	global_store_dwordx4 v203, v[34:37], s[24:25] offset:528
	s_waitcnt vmcnt(16)
	v_pk_fma_f32 v[30:31], v[30:31], 0.5, v[178:179] op_sel_hi:[1,0,1]
	v_pk_fma_f32 v[32:33], v[32:33], 0.5, v[180:181] op_sel_hi:[1,0,1]
	v_pk_fma_f32 v[26:27], v[26:27], 0.5, v[182:183] op_sel_hi:[1,0,1]
	v_pk_fma_f32 v[28:29], v[28:29], 0.5, v[184:185] op_sel_hi:[1,0,1]
	v_pk_fma_f32 v[22:23], v[22:23], 0.5, v[224:225] op_sel_hi:[1,0,1]
	v_pk_fma_f32 v[24:25], v[24:25], 0.5, v[226:227] op_sel_hi:[1,0,1]
	v_pk_fma_f32 v[18:19], v[18:19], 0.5, v[228:229] op_sel_hi:[1,0,1]
	v_pk_fma_f32 v[20:21], v[20:21], 0.5, v[230:231] op_sel_hi:[1,0,1]
	global_store_dwordx4 v248, v[30:33], s[24:25]
	global_store_dwordx4 v248, v[26:29], s[24:25] offset:16
	global_store_dwordx4 v248, v[22:25], s[24:25] offset:512
	global_store_dwordx4 v248, v[18:21], s[24:25] offset:528
	s_waitcnt vmcnt(12)
	v_pk_fma_f32 v[14:15], v[14:15], 0.5, v[232:233] op_sel_hi:[1,0,1]
	v_pk_fma_f32 v[16:17], v[16:17], 0.5, v[234:235] op_sel_hi:[1,0,1]
	v_pk_fma_f32 v[10:11], v[10:11], 0.5, v[236:237] op_sel_hi:[1,0,1]
	v_pk_fma_f32 v[12:13], v[12:13], 0.5, v[238:239] op_sel_hi:[1,0,1]
	v_pk_fma_f32 v[6:7], v[6:7], 0.5, v[240:241] op_sel_hi:[1,0,1]
	v_pk_fma_f32 v[8:9], v[8:9], 0.5, v[242:243] op_sel_hi:[1,0,1]
	v_pk_fma_f32 v[2:3], v[2:3], 0.5, v[244:245] op_sel_hi:[1,0,1]
	v_pk_fma_f32 v[4:5], v[4:5], 0.5, v[246:247] op_sel_hi:[1,0,1]
	global_store_dwordx4 v249, v[14:17], s[24:25]
	global_store_dwordx4 v249, v[10:13], s[24:25] offset:16
	global_store_dwordx4 v249, v[6:9], s[24:25] offset:512
	global_store_dwordx4 v249, v[2:5], s[24:25] offset:528
	s_cbranch_vccnz .LBB0_523
	s_andn2_b64 vcc, exec, s[44:45]
	s_cbranch_vccnz .LBB0_522
	s_barrier
	s_branch .LBB0_522

.LBB0_1541:
	v_mov_b32_e32 v140, v142
	v_lshl_or_b32 v146, s65, 8, v144
	v_lshl_add_u32 v140, s66, 8, v140
	v_lshl_add_u32 v140, v140, 10, v146
	v_lshlrev_b32_e32 v140, 2, v140
	s_mov_b64 s[8:9], 0xb0000
	s_mov_b64 s[52:53], -1
	s_andn2_b64 vcc, exec, s[38:39]
	v_add_u32_e32 v141, 0x10000, v140
	v_add_u32_e32 v186, 0x20000, v140
	v_add_u32_e32 v187, 0x30000, v140
	v_add_u32_e32 v202, 0x80000, v140
	v_add_u32_e32 v203, 0x90000, v140
	v_add_u32_e32 v248, 0xa0000, v140
	v_add_u32_e32 v249, 0xb0000, v140
	global_load_dwordx4 v[146:149], v140, s[24:25]
	global_load_dwordx4 v[150:153], v140, s[24:25] offset:16
	global_load_dwordx4 v[154:157], v140, s[24:25] offset:512
	global_load_dwordx4 v[158:161], v140, s[24:25] offset:528
	global_load_dwordx4 v[162:165], v141, s[24:25]
	global_load_dwordx4 v[166:169], v141, s[24:25] offset:16
	global_load_dwordx4 v[170:173], v141, s[24:25] offset:512
	global_load_dwordx4 v[174:177], v141, s[24:25] offset:528
	global_load_dwordx4 v[178:181], v186, s[24:25]
	global_load_dwordx4 v[182:185], v186, s[24:25] offset:16
	global_load_dwordx4 v[224:227], v186, s[24:25] offset:512
	global_load_dwordx4 v[228:231], v186, s[24:25] offset:528
	global_load_dwordx4 v[232:235], v187, s[24:25]
	global_load_dwordx4 v[236:239], v187, s[24:25] offset:16
	global_load_dwordx4 v[240:243], v187, s[24:25] offset:512
	global_load_dwordx4 v[244:247], v187, s[24:25] offset:528
	s_waitcnt vmcnt(12)
	v_pk_add_f32 v[126:127], v[126:127], v[146:147]
	v_pk_add_f32 v[128:129], v[128:129], v[148:149]
	v_pk_add_f32 v[122:123], v[122:123], v[150:151]
	v_pk_add_f32 v[124:125], v[124:125], v[152:153]
	v_pk_add_f32 v[118:119], v[118:119], v[154:155]
	v_pk_add_f32 v[120:121], v[120:121], v[156:157]
	v_pk_add_f32 v[114:115], v[114:115], v[158:159]
	v_pk_add_f32 v[116:117], v[116:117], v[160:161]
	global_store_dwordx4 v140, v[126:129], s[24:25]
	global_store_dwordx4 v140, v[122:125], s[24:25] offset:16
	global_store_dwordx4 v140, v[118:121], s[24:25] offset:512
	global_store_dwordx4 v140, v[114:117], s[24:25] offset:528
	global_load_dwordx4 v[146:149], v202, s[24:25]
	global_load_dwordx4 v[150:153], v202, s[24:25] offset:16
	global_load_dwordx4 v[154:157], v202, s[24:25] offset:512
	global_load_dwordx4 v[158:161], v202, s[24:25] offset:528
	s_waitcnt vmcnt(16)
	v_pk_add_f32 v[110:111], v[110:111], v[162:163]
	v_pk_add_f32 v[112:113], v[112:113], v[164:165]
	v_pk_add_f32 v[106:107], v[106:107], v[166:167]
	v_pk_add_f32 v[108:109], v[108:109], v[168:169]
	v_pk_add_f32 v[94:95], v[94:95], v[170:171]
	v_pk_add_f32 v[96:97], v[96:97], v[172:173]
	v_pk_add_f32 v[90:91], v[90:91], v[174:175]
	v_pk_add_f32 v[92:93], v[92:93], v[176:177]
	global_store_dwordx4 v141, v[110:113], s[24:25]
	global_store_dwordx4 v141, v[106:109], s[24:25] offset:16
	global_store_dwordx4 v141, v[94:97], s[24:25] offset:512
	global_store_dwordx4 v141, v[90:93], s[24:25] offset:528
	global_load_dwordx4 v[162:165], v203, s[24:25]
	global_load_dwordx4 v[166:169], v203, s[24:25] offset:16
	global_load_dwordx4 v[170:173], v203, s[24:25] offset:512
	global_load_dwordx4 v[174:177], v203, s[24:25] offset:528
	s_waitcnt vmcnt(20)
	v_pk_add_f32 v[102:103], v[102:103], v[178:179]
	v_pk_add_f32 v[104:105], v[104:105], v[180:181]
	v_pk_add_f32 v[98:99], v[98:99], v[182:183]
	v_pk_add_f32 v[100:101], v[100:101], v[184:185]
	v_pk_add_f32 v[86:87], v[86:87], v[224:225]
	v_pk_add_f32 v[88:89], v[88:89], v[226:227]
	v_pk_add_f32 v[82:83], v[82:83], v[228:229]
	v_pk_add_f32 v[84:85], v[84:85], v[230:231]
	global_store_dwordx4 v186, v[102:105], s[24:25]
	global_store_dwordx4 v186, v[98:101], s[24:25] offset:16
	global_store_dwordx4 v186, v[86:89], s[24:25] offset:512
	global_store_dwordx4 v186, v[82:85], s[24:25] offset:528
	global_load_dwordx4 v[178:181], v248, s[24:25]
	global_load_dwordx4 v[182:185], v248, s[24:25] offset:16
	global_load_dwordx4 v[224:227], v248, s[24:25] offset:512
	global_load_dwordx4 v[228:231], v248, s[24:25] offset:528
	s_waitcnt vmcnt(24)
	v_pk_add_f32 v[78:79], v[78:79], v[232:233]
	v_pk_add_f32 v[80:81], v[80:81], v[234:235]
	v_pk_add_f32 v[74:75], v[74:75], v[236:237]
	v_pk_add_f32 v[76:77], v[76:77], v[238:239]
	v_pk_add_f32 v[70:71], v[70:71], v[240:241]
	v_pk_add_f32 v[72:73], v[72:73], v[242:243]
	v_pk_add_f32 v[66:67], v[66:67], v[244:245]
	v_pk_add_f32 v[68:69], v[68:69], v[246:247]
	global_store_dwordx4 v187, v[78:81], s[24:25]
	global_store_dwordx4 v187, v[74:77], s[24:25] offset:16
	global_store_dwordx4 v187, v[70:73], s[24:25] offset:512
	global_store_dwordx4 v187, v[66:69], s[24:25] offset:528
	global_load_dwordx4 v[232:235], v249, s[24:25]
	global_load_dwordx4 v[236:239], v249, s[24:25] offset:16
	global_load_dwordx4 v[240:243], v249, s[24:25] offset:512
	global_load_dwordx4 v[244:247], v249, s[24:25] offset:528
	s_waitcnt vmcnt(24)
	v_pk_add_f32 v[62:63], v[62:63], v[146:147]
	v_pk_add_f32 v[64:65], v[64:65], v[148:149]
	v_pk_add_f32 v[58:59], v[58:59], v[150:151]
	v_pk_add_f32 v[60:61], v[60:61], v[152:153]
	v_pk_add_f32 v[54:55], v[54:55], v[154:155]
	v_pk_add_f32 v[56:57], v[56:57], v[156:157]
	v_pk_add_f32 v[50:51], v[50:51], v[158:159]
	v_pk_add_f32 v[52:53], v[52:53], v[160:161]
	global_store_dwordx4 v202, v[62:65], s[24:25]
	global_store_dwordx4 v202, v[58:61], s[24:25] offset:16
	global_store_dwordx4 v202, v[54:57], s[24:25] offset:512
	global_store_dwordx4 v202, v[50:53], s[24:25] offset:528
	s_waitcnt vmcnt(20)
	v_pk_add_f32 v[46:47], v[46:47], v[162:163]
	v_pk_add_f32 v[48:49], v[48:49], v[164:165]
	v_pk_add_f32 v[42:43], v[42:43], v[166:167]
	v_pk_add_f32 v[44:45], v[44:45], v[168:169]
	v_pk_add_f32 v[38:39], v[38:39], v[170:171]
	v_pk_add_f32 v[40:41], v[40:41], v[172:173]
	v_pk_add_f32 v[34:35], v[34:35], v[174:175]
	v_pk_add_f32 v[36:37], v[36:37], v[176:177]
	global_store_dwordx4 v203, v[46:49], s[24:25]
	global_store_dwordx4 v203, v[42:45], s[24:25] offset:16
	global_store_dwordx4 v203, v[38:41], s[24:25] offset:512
	global_store_dwordx4 v203, v[34:37], s[24:25] offset:528
	s_waitcnt vmcnt(16)
	v_pk_add_f32 v[30:31], v[30:31], v[178:179]
	v_pk_add_f32 v[32:33], v[32:33], v[180:181]
	v_pk_add_f32 v[26:27], v[26:27], v[182:183]
	v_pk_add_f32 v[28:29], v[28:29], v[184:185]
	v_pk_add_f32 v[22:23], v[22:23], v[224:225]
	v_pk_add_f32 v[24:25], v[24:25], v[226:227]
	v_pk_add_f32 v[18:19], v[18:19], v[228:229]
	v_pk_add_f32 v[20:21], v[20:21], v[230:231]
	global_store_dwordx4 v248, v[30:33], s[24:25]
	global_store_dwordx4 v248, v[26:29], s[24:25] offset:16
	global_store_dwordx4 v248, v[22:25], s[24:25] offset:512
	global_store_dwordx4 v248, v[18:21], s[24:25] offset:528
	s_waitcnt vmcnt(12)
	v_pk_add_f32 v[14:15], v[14:15], v[232:233]
	v_pk_add_f32 v[16:17], v[16:17], v[234:235]
	v_pk_add_f32 v[10:11], v[10:11], v[236:237]
	v_pk_add_f32 v[12:13], v[12:13], v[238:239]
	v_pk_add_f32 v[6:7], v[6:7], v[240:241]
	v_pk_add_f32 v[8:9], v[8:9], v[242:243]
	v_pk_add_f32 v[2:3], v[2:3], v[244:245]
	v_pk_add_f32 v[4:5], v[4:5], v[246:247]
	global_store_dwordx4 v249, v[14:17], s[24:25]
	global_store_dwordx4 v249, v[10:13], s[24:25] offset:16
	global_store_dwordx4 v249, v[6:9], s[24:25] offset:512
	global_store_dwordx4 v249, v[2:5], s[24:25] offset:528
	s_cbranch_vccnz .LBB0_1530
	s_andn2_b64 vcc, exec, s[40:41]
	s_cbranch_vccnz .LBB0_1529
	s_barrier
	s_branch .LBB0_1529
